# residual-add GEMM epilogues: each store issued right behind the adds that produce its data (mixer output projection had all stores at the end of a round), counted waits recomputed
# speedup vs baseline: 1.0032x; 1.0032x over previous
;     __device__ __forceinline__ void operator()(const f32x4 (&acc)[2][2][4][2], const pg8::Unit& u, int wr, int wc, int fr, int fq) const {
;         const int row0 = u.pm * 256 + wr * 64 + fr, col0 = u.pn * 256 + wc * 32 + 4 * fq;
; #pragma unroll
;         for (int ai = 0; ai < 2; ++ai)
; #pragma unroll
;             for (int mh = 0; mh < 2; ++mh) {
;                 f32x4 xi[2][2][2];
; #pragma unroll
;                 for (int m = 0; m < 2; ++m)
; #pragma unroll
;                     for (int bj = 0; bj < 2; ++bj)
; #pragma unroll
;                         for (int n = 0; n < 2; ++n) xi[m][bj][n] = *(const f32x4*)(Xin + (size_t)(row0 + ai * 128 + (2 * mh + m) * 16) * D + col0 + bj * 128 + n * 16);
;                 __builtin_amdgcn_sched_barrier(0);
; #pragma unroll
;                 for (int m = 0; m < 2; ++m)
; #pragma unroll
;                     for (int bj = 0; bj < 2; ++bj)
; #pragma unroll
;                         for (int n = 0; n < 2; ++n) *(f32x4*)(Xout + (size_t)(row0 + ai * 128 + (2 * mh + m) * 16) * D + col0 + bj * 128 + n * 16) = xi[m][bj][n] + acc[ai][bj][2 * mh + m][n] * scale;
.LBB0_121:
	v_lshl_or_b32 v16, s30, 8, v148
	v_lshl_add_u32 v26, s31, 8, v146
	v_ashrrev_i32_e32 v17, 31, v16
	v_readlane_b32 s2, v254, 52
	v_lshlrev_b64 v[16:17], 2, v[16:17]
	v_readlane_b32 s3, v254, 53
	v_ashrrev_i32_e32 v27, 31, v26
	v_lshlrev_b64 v[24:25], 12, v[26:27]
	v_lshl_add_u64 v[18:19], s[2:3], 0, v[16:17]
	v_lshl_add_u64 v[150:151], v[18:19], 0, v[24:25]
	global_load_dwordx4 v[40:43], v[150:151], off
	global_load_dwordx4 v[168:171], v[150:151], off offset:64
	global_load_dwordx4 v[172:175], v[150:151], off offset:512
	global_load_dwordx4 v[176:179], v[150:151], off offset:576
	v_or_b32_e32 v150, 16, v26
	v_ashrrev_i32_e32 v151, 31, v150
	v_lshlrev_b64 v[150:151], 12, v[150:151]
	v_lshl_add_u64 v[158:159], v[18:19], 0, v[150:151]
	global_load_dwordx4 v[180:183], v[158:159], off
	global_load_dwordx4 v[184:187], v[158:159], off offset:64
	global_load_dwordx4 v[188:191], v[158:159], off offset:512
	global_load_dwordx4 v[192:195], v[158:159], off offset:576
	s_waitcnt vmcnt(7)
	v_pk_add_f32 v[42:43], v[134:135], v[42:43]
	v_lshl_add_u64 v[134:135], s[2:3], 0, v[24:25]
	v_pk_add_f32 v[40:41], v[136:137], v[40:41]
	v_lshl_add_u64 v[134:135], v[134:135], 0, v[16:17]
	global_store_dwordx4 v[134:135], v[40:43], off
	s_nop 1
	s_waitcnt vmcnt(7)
	v_pk_add_f32 v[42:43], v[126:127], v[170:171]
	v_pk_add_f32 v[40:41], v[124:125], v[168:169]
	global_store_dwordx4 v[134:135], v[40:43], off offset:64
	s_nop 1
	s_waitcnt vmcnt(7)
	v_pk_add_f32 v[42:43], v[144:145], v[174:175]
	v_pk_add_f32 v[40:41], v[142:143], v[172:173]
	global_store_dwordx4 v[134:135], v[40:43], off offset:512
	s_nop 1
	s_waitcnt vmcnt(7)
	v_pk_add_f32 v[42:43], v[140:141], v[178:179]
	v_pk_add_f32 v[40:41], v[138:139], v[176:177]
	global_store_dwordx4 v[134:135], v[40:43], off offset:576
	s_nop 1
	s_waitcnt vmcnt(7)
	v_pk_add_f32 v[40:41], v[116:117], v[180:181]
	v_lshl_add_u64 v[116:117], s[2:3], 0, v[150:151]
	v_pk_add_f32 v[42:43], v[118:119], v[182:183]
	v_lshl_add_u64 v[116:117], v[116:117], 0, v[16:17]
	global_store_dwordx4 v[116:117], v[40:43], off
	s_nop 1
	s_waitcnt vmcnt(7)
	v_pk_add_f32 v[42:43], v[110:111], v[186:187]
	v_pk_add_f32 v[40:41], v[108:109], v[184:185]
	global_store_dwordx4 v[116:117], v[40:43], off offset:64
	s_nop 1
	s_waitcnt vmcnt(7)
	v_pk_add_f32 v[42:43], v[122:123], v[190:191]
	v_pk_add_f32 v[40:41], v[120:121], v[188:189]
	global_store_dwordx4 v[116:117], v[40:43], off offset:512
	s_nop 1
	s_waitcnt vmcnt(7)
	v_pk_add_f32 v[42:43], v[114:115], v[194:195]
	v_pk_add_f32 v[40:41], v[112:113], v[192:193]
	global_store_dwordx4 v[116:117], v[40:43], off offset:576
	s_nop 1
	v_or_b32_e32 v40, 32, v26
	v_or_b32_e32 v26, 48, v26
	v_ashrrev_i32_e32 v41, 31, v40
	v_ashrrev_i32_e32 v27, 31, v26
	v_lshlrev_b64 v[142:143], 12, v[40:41]
	v_lshlrev_b64 v[26:27], 12, v[26:27]
	v_lshl_add_u64 v[116:117], v[18:19], 0, v[142:143]
	v_lshl_add_u64 v[138:139], v[18:19], 0, v[26:27]
	global_load_dwordx4 v[40:43], v[116:117], off
	global_load_dwordx4 v[108:111], v[116:117], off offset:64
	global_load_dwordx4 v[112:115], v[116:117], off offset:512
	s_nop 0
	global_load_dwordx4 v[116:119], v[116:117], off offset:576
	s_nop 0
	global_load_dwordx4 v[120:123], v[138:139], off
	global_load_dwordx4 v[124:127], v[138:139], off offset:64
	global_load_dwordx4 v[134:137], v[138:139], off offset:512
	s_nop 0
	global_load_dwordx4 v[138:141], v[138:139], off offset:576
	s_waitcnt vmcnt(7)
	v_pk_add_f32 v[40:41], v[100:101], v[40:41]
	v_lshl_add_u64 v[100:101], s[2:3], 0, v[142:143]
	v_pk_add_f32 v[42:43], v[102:103], v[42:43]
	v_lshl_add_u64 v[100:101], v[100:101], 0, v[16:17]
	global_store_dwordx4 v[100:101], v[40:43], off
	v_lshl_add_u64 v[26:27], s[2:3], 0, v[26:27]
	v_lshl_add_u64 v[26:27], v[26:27], 0, v[16:17]
	s_waitcnt vmcnt(7)
	v_pk_add_f32 v[42:43], v[94:95], v[110:111]
	v_pk_add_f32 v[40:41], v[92:93], v[108:109]
	global_store_dwordx4 v[100:101], v[40:43], off offset:64
	s_nop 1
	s_waitcnt vmcnt(7)
	v_pk_add_f32 v[42:43], v[106:107], v[114:115]
	v_pk_add_f32 v[40:41], v[104:105], v[112:113]
	global_store_dwordx4 v[100:101], v[40:43], off offset:512
	s_nop 1
	s_waitcnt vmcnt(7)
	v_pk_add_f32 v[42:43], v[98:99], v[118:119]
	v_pk_add_f32 v[40:41], v[96:97], v[116:117]
	global_store_dwordx4 v[100:101], v[40:43], off offset:576
	s_nop 1
	s_waitcnt vmcnt(7)
	v_pk_add_f32 v[42:43], v[86:87], v[122:123]
	v_pk_add_f32 v[40:41], v[84:85], v[120:121]
	global_store_dwordx4 v[26:27], v[40:43], off
	s_nop 1
	s_waitcnt vmcnt(7)
	v_pk_add_f32 v[42:43], v[74:75], v[126:127]
	v_pk_add_f32 v[40:41], v[72:73], v[124:125]
	global_store_dwordx4 v[26:27], v[40:43], off offset:64
	s_nop 1
	s_waitcnt vmcnt(7)
	v_pk_add_f32 v[42:43], v[90:91], v[136:137]
	v_pk_add_f32 v[40:41], v[88:89], v[134:135]
	global_store_dwordx4 v[26:27], v[40:43], off offset:512
	s_nop 1
	s_waitcnt vmcnt(7)
; #define PG8_BAR __builtin_amdgcn_s_barrier()
; template <class Epi, class Sched, bool ALIGN_EPI = false, bool SP2 = false>
; __device__ __forceinline__ void gemm_phase(PG8_LAS unsigned char* lds, const Gemm g, const Sched& S, const Epi& E) {
;     ...
;         if constexpr (ALIGN_EPI) { if (wr == 0) PG8_BAR; }
;         if constexpr (!Epi::AFTER_DRAIN) { E(acc, cur, wr, wc, fr, fq); S.done(cur); }
;         if (!has_next) break;
; #pragma unroll
;         for (int a = 0; a < 2; ++a)
; #pragma unroll
;             for (int b = 0; b < 2; ++b)
; #pragma unroll
;                 for (int m = 0; m < 4; ++m)
; #pragma unroll
;                     for (int n = 0; n < 2; ++n) acc[a][b][m][n] = (f32x4){0.f, 0.f, 0.f, 0.f};
;         cur = nxt; cA = nA; cB = nB; ++ui;
;         if constexpr (ALIGN_EPI) { if (wr == 1) PG8_BAR; }
;     __device__ __forceinline__ void operator()(const f32x4 (&acc)[2][2][4][2], const pg8::Unit& u, int wr, int wc, int fr, int fq) const {
;     ...
;         for (int ai = 0; ai < 2; ++ai)
; #pragma unroll
;             for (int mh = 0; mh < 2; ++mh) {
;                 f32x4 xi[2][2][2];
; #pragma unroll
;                 for (int m = 0; m < 2; ++m)
; #pragma unroll
;                     for (int bj = 0; bj < 2; ++bj)
; #pragma unroll
;                         for (int n = 0; n < 2; ++n) xi[m][bj][n] = *(const f32x4*)(Xin + (size_t)(row0 + ai * 128 + (2 * mh + m) * 16) * D + col0 + bj * 128 + n * 16);
;                 __builtin_amdgcn_sched_barrier(0);
; #pragma unroll
;                 for (int m = 0; m < 2; ++m)
; #pragma unroll
;                     for (int bj = 0; bj < 2; ++bj)
; #pragma unroll
;                         for (int n = 0; n < 2; ++n) *(f32x4*)(Xout + (size_t)(row0 + ai * 128 + (2 * mh + m) * 16) * D + col0 + bj * 128 + n * 16) = xi[m][bj][n] + acc[ai][bj][2 * mh + m][n] * scale;
;                 __builtin_amdgcn_sched_barrier(0);
;             }
	v_pk_add_f32 v[42:43], v[82:83], v[140:141]
	v_pk_add_f32 v[40:41], v[80:81], v[138:139]
	global_store_dwordx4 v[26:27], v[40:43], off offset:576
	s_mov_b64 s[0:1], 0x80000
	v_lshl_add_u64 v[26:27], v[24:25], 0, s[0:1]
	s_mov_b64 s[0:1], 0x90000
	v_lshl_add_u64 v[104:105], v[24:25], 0, s[0:1]
	v_lshl_add_u64 v[84:85], v[18:19], 0, v[26:27]
	v_lshl_add_u64 v[100:101], v[18:19], 0, v[104:105]
	global_load_dwordx4 v[40:43], v[84:85], off
	global_load_dwordx4 v[72:75], v[84:85], off offset:64
	global_load_dwordx4 v[80:83], v[84:85], off offset:512
	s_nop 0
	global_load_dwordx4 v[84:87], v[84:85], off offset:576
	s_nop 0
	global_load_dwordx4 v[88:91], v[100:101], off
	global_load_dwordx4 v[92:95], v[100:101], off offset:64
	global_load_dwordx4 v[96:99], v[100:101], off offset:512
	s_nop 0
	global_load_dwordx4 v[100:103], v[100:101], off offset:576
	v_lshl_add_u64 v[26:27], s[2:3], 0, v[26:27]
	s_waitcnt vmcnt(7)
	v_pk_add_f32 v[42:43], v[66:67], v[42:43]
	v_pk_add_f32 v[40:41], v[64:65], v[40:41]
	v_lshl_add_u64 v[26:27], v[26:27], 0, v[16:17]
	global_store_dwordx4 v[26:27], v[40:43], off
	s_nop 1
	s_waitcnt vmcnt(7)
	v_pk_add_f32 v[42:43], v[62:63], v[74:75]
	v_pk_add_f32 v[40:41], v[60:61], v[72:73]
	global_store_dwordx4 v[26:27], v[40:43], off offset:64
	s_nop 1
	s_waitcnt vmcnt(7)
	v_pk_add_f32 v[42:43], v[78:79], v[82:83]
	v_pk_add_f32 v[40:41], v[76:77], v[80:81]
	global_store_dwordx4 v[26:27], v[40:43], off offset:512
	s_nop 1
	s_waitcnt vmcnt(7)
	v_pk_add_f32 v[42:43], v[70:71], v[86:87]
	v_pk_add_f32 v[40:41], v[68:69], v[84:85]
	global_store_dwordx4 v[26:27], v[40:43], off offset:576
	v_lshl_add_u64 v[26:27], s[2:3], 0, v[104:105]
	v_lshl_add_u64 v[26:27], v[26:27], 0, v[16:17]
	s_waitcnt vmcnt(7)
	v_pk_add_f32 v[42:43], v[54:55], v[90:91]
	v_pk_add_f32 v[40:41], v[52:53], v[88:89]
	global_store_dwordx4 v[26:27], v[40:43], off
	s_nop 1
	s_waitcnt vmcnt(7)
	v_pk_add_f32 v[42:43], v[46:47], v[94:95]
	v_pk_add_f32 v[40:41], v[44:45], v[92:93]
	global_store_dwordx4 v[26:27], v[40:43], off offset:64
	s_nop 1
	s_waitcnt vmcnt(7)
	v_pk_add_f32 v[42:43], v[58:59], v[98:99]
	v_pk_add_f32 v[40:41], v[56:57], v[96:97]
	global_store_dwordx4 v[26:27], v[40:43], off offset:512
	s_nop 1
	s_waitcnt vmcnt(7)
	v_pk_add_f32 v[42:43], v[50:51], v[102:103]
	v_pk_add_f32 v[40:41], v[48:49], v[100:101]
	global_store_dwordx4 v[26:27], v[40:43], off offset:576
	s_mov_b64 s[0:1], 0xa0000
	v_lshl_add_u64 v[68:69], v[24:25], 0, s[0:1]
	s_mov_b64 s[0:1], 0xb0000
	v_lshl_add_u64 v[70:71], v[24:25], 0, s[0:1]
	v_lshl_add_u64 v[26:27], v[18:19], 0, v[68:69]
	v_lshl_add_u64 v[18:19], v[18:19], 0, v[70:71]
	global_load_dwordx4 v[40:43], v[26:27], off
	global_load_dwordx4 v[44:47], v[26:27], off offset:64
	global_load_dwordx4 v[48:51], v[26:27], off offset:512
	global_load_dwordx4 v[52:55], v[26:27], off offset:576
	s_nop 0
	global_load_dwordx4 v[24:27], v[18:19], off
	global_load_dwordx4 v[56:59], v[18:19], off offset:64
	global_load_dwordx4 v[60:63], v[18:19], off offset:512
	global_load_dwordx4 v[64:67], v[18:19], off offset:576
	v_lshl_add_u64 v[18:19], s[2:3], 0, v[68:69]
	s_waitcnt vmcnt(7)
	v_pk_add_f32 v[28:29], v[28:29], v[40:41]
	v_lshl_add_u64 v[40:41], v[18:19], 0, v[16:17]
	s_waitcnt vmcnt(6)
	v_pk_add_f32 v[22:23], v[22:23], v[46:47]
	v_pk_add_f32 v[20:21], v[20:21], v[44:45]
	global_store_dwordx4 v[40:41], v[20:23], off offset:64
	s_waitcnt vmcnt(6)
	v_pk_add_f32 v[18:19], v[36:37], v[48:49]
	v_pk_add_f32 v[30:31], v[30:31], v[42:43]
	v_pk_add_f32 v[20:21], v[38:39], v[50:51]
	global_store_dwordx4 v[40:41], v[18:21], off offset:512
	s_waitcnt vmcnt(5)
	v_pk_add_f32 v[14:15], v[14:15], v[26:27]
	v_pk_add_f32 v[12:13], v[12:13], v[24:25]
	v_pk_add_f32 v[20:21], v[34:35], v[54:55]
	v_pk_add_f32 v[18:19], v[32:33], v[52:53]
	global_store_dwordx4 v[40:41], v[18:21], off offset:576
	global_store_dwordx4 v[40:41], v[28:31], off
	s_waitcnt vmcnt(6)
	v_pk_add_f32 v[10:11], v[10:11], v[58:59]
	v_pk_add_f32 v[8:9], v[8:9], v[56:57]
	v_lshl_add_u64 v[18:19], s[2:3], 0, v[70:71]
	v_lshl_add_u64 v[16:17], v[18:19], 0, v[16:17]
	global_store_dwordx4 v[16:17], v[12:15], off
	global_store_dwordx4 v[16:17], v[8:11], off offset:64
	s_waitcnt vmcnt(7)
	v_pk_add_f32 v[6:7], v[6:7], v[62:63]
	v_pk_add_f32 v[4:5], v[4:5], v[60:61]
	global_store_dwordx4 v[16:17], v[4:7], off offset:512
	s_waitcnt vmcnt(7)
	v_pk_add_f32 v[2:3], v[2:3], v[66:67]
	v_pk_add_f32 v[0:1], v[0:1], v[64:65]
	global_store_dwordx4 v[16:17], v[0:3], off offset:576
	s_and_b64 vcc, exec, s[4:5]
	s_mov_b64 s[0:1], -1
	s_cbranch_vccnz .LBB0_104
	s_andn2_b64 vcc, exec, s[16:17]
	s_cbranch_vccnz .LBB0_103
	s_barrier
	s_branch .LBB0_103

;     __device__ __forceinline__ void operator()(const f32x4 (&acc)[2][2][4][2], const pg8::Unit& u, int wr, int wc, int fr, int fq) const {
;         const int row0 = u.pm * 256 + wr * 64 + fr, col0 = u.pn * 256 + wc * 32 + 4 * fq;
; #pragma unroll
;         for (int ai = 0; ai < 2; ++ai)
; #pragma unroll
;             for (int mh = 0; mh < 2; ++mh) {
;                 f32x4 xi[2][2][2];
; #pragma unroll
;                 for (int m = 0; m < 2; ++m)
; #pragma unroll
;                     for (int bj = 0; bj < 2; ++bj)
; #pragma unroll
;                         for (int n = 0; n < 2; ++n) xi[m][bj][n] = *(const f32x4*)(Xin + (size_t)(row0 + ai * 128 + (2 * mh + m) * 16) * D + col0 + bj * 128 + n * 16);
;                 __builtin_amdgcn_sched_barrier(0);
; #pragma unroll
;                 for (int m = 0; m < 2; ++m)
; #pragma unroll
;                     for (int bj = 0; bj < 2; ++bj)
; #pragma unroll
;                         for (int n = 0; n < 2; ++n) *(f32x4*)(Xout + (size_t)(row0 + ai * 128 + (2 * mh + m) * 16) * D + col0 + bj * 128 + n * 16) = xi[m][bj][n] + acc[ai][bj][2 * mh + m][n] * scale;
.LBB0_161:
	v_lshl_add_u32 v184, s35, 8, v140
	v_lshl_or_b32 v134, s34, 8, v142
	v_ashrrev_i32_e32 v135, 31, v134
	v_readlane_b32 s2, v254, 52
	v_or_b32_e32 v168, 16, v184
	v_lshlrev_b64 v[134:135], 2, v[134:135]
	v_readlane_b32 s3, v254, 53
	v_ashrrev_i32_e32 v185, 31, v184
	v_ashrrev_i32_e32 v169, 31, v168
	v_lshl_add_u64 v[136:137], s[2:3], 0, v[134:135]
	v_lshlrev_b64 v[138:139], 12, v[184:185]
	v_lshlrev_b64 v[186:187], 12, v[168:169]
	v_lshl_add_u64 v[162:163], v[136:137], 0, v[138:139]
	v_lshl_add_u64 v[180:181], v[136:137], 0, v[186:187]
	global_load_dwordx4 v[144:147], v[162:163], off
	global_load_dwordx4 v[148:151], v[162:163], off offset:64
	global_load_dwordx4 v[158:161], v[162:163], off offset:512
	s_nop 0
	global_load_dwordx4 v[162:165], v[162:163], off offset:576
	s_nop 0
	global_load_dwordx4 v[168:171], v[180:181], off
	global_load_dwordx4 v[172:175], v[180:181], off offset:64
	global_load_dwordx4 v[176:179], v[180:181], off offset:512
	s_nop 0
	global_load_dwordx4 v[180:183], v[180:181], off offset:576
	s_waitcnt vmcnt(7)
	v_pk_add_f32 v[124:125], v[124:125], v[144:145]
	v_lshl_add_u64 v[144:145], s[2:3], 0, v[138:139]
	v_lshl_add_u64 v[144:145], v[144:145], 0, v[134:135]
	s_waitcnt vmcnt(4)
	v_pk_add_f32 v[114:115], v[114:115], v[164:165]
	v_pk_add_f32 v[112:113], v[112:113], v[162:163]
	global_store_dwordx4 v[144:145], v[112:115], off offset:576
	v_pk_add_f32 v[126:127], v[126:127], v[146:147]
	global_store_dwordx4 v[144:145], v[124:127], off
	v_pk_add_f32 v[122:123], v[122:123], v[150:151]
	v_lshl_add_u64 v[112:113], s[2:3], 0, v[186:187]
	v_pk_add_f32 v[120:121], v[120:121], v[148:149]
	global_store_dwordx4 v[144:145], v[120:123], off offset:64
	v_pk_add_f32 v[118:119], v[118:119], v[160:161]
	v_pk_add_f32 v[116:117], v[116:117], v[158:159]
	global_store_dwordx4 v[144:145], v[116:119], off offset:512
	s_waitcnt vmcnt(7)
	v_pk_add_f32 v[110:111], v[110:111], v[170:171]
	v_pk_add_f32 v[108:109], v[108:109], v[168:169]
	v_lshl_add_u64 v[112:113], v[112:113], 0, v[134:135]
	global_store_dwordx4 v[112:113], v[108:111], off
	s_waitcnt vmcnt(7)
	v_pk_add_f32 v[106:107], v[106:107], v[174:175]
	v_pk_add_f32 v[104:105], v[104:105], v[172:173]
	global_store_dwordx4 v[112:113], v[104:107], off offset:64
	s_waitcnt vmcnt(7)
	v_pk_add_f32 v[102:103], v[102:103], v[178:179]
	v_pk_add_f32 v[100:101], v[100:101], v[176:177]
	global_store_dwordx4 v[112:113], v[100:103], off offset:512
	s_waitcnt vmcnt(7)
	v_pk_add_f32 v[98:99], v[98:99], v[182:183]
	v_pk_add_f32 v[96:97], v[96:97], v[180:181]
	global_store_dwordx4 v[112:113], v[96:99], off offset:576
	s_nop 1
	v_or_b32_e32 v96, 32, v184
	v_or_b32_e32 v112, 48, v184
	v_ashrrev_i32_e32 v97, 31, v96
	v_ashrrev_i32_e32 v113, 31, v112
	v_lshlrev_b64 v[144:145], 12, v[96:97]
	v_lshlrev_b64 v[146:147], 12, v[112:113]
	v_lshl_add_u64 v[108:109], v[136:137], 0, v[144:145]
	v_lshl_add_u64 v[124:125], v[136:137], 0, v[146:147]
	global_load_dwordx4 v[96:99], v[108:109], off
	global_load_dwordx4 v[100:103], v[108:109], off offset:64
	global_load_dwordx4 v[104:107], v[108:109], off offset:512
	s_nop 0
	global_load_dwordx4 v[108:111], v[108:109], off offset:576
	s_nop 0
	global_load_dwordx4 v[112:115], v[124:125], off
	global_load_dwordx4 v[116:119], v[124:125], off offset:64
	global_load_dwordx4 v[120:123], v[124:125], off offset:512
	s_nop 0
	global_load_dwordx4 v[124:127], v[124:125], off offset:576
	s_waitcnt vmcnt(7)
	v_pk_add_f32 v[92:93], v[92:93], v[96:97]
	v_lshl_add_u64 v[96:97], s[2:3], 0, v[144:145]
	v_lshl_add_u64 v[96:97], v[96:97], 0, v[134:135]
	s_waitcnt vmcnt(4)
	v_pk_add_f32 v[82:83], v[82:83], v[110:111]
	v_pk_add_f32 v[80:81], v[80:81], v[108:109]
	global_store_dwordx4 v[96:97], v[80:83], off offset:576
	v_pk_add_f32 v[94:95], v[94:95], v[98:99]
	global_store_dwordx4 v[96:97], v[92:95], off
	v_pk_add_f32 v[90:91], v[90:91], v[102:103]
	v_lshl_add_u64 v[80:81], s[2:3], 0, v[146:147]
	v_pk_add_f32 v[88:89], v[88:89], v[100:101]
	global_store_dwordx4 v[96:97], v[88:91], off offset:64
	v_pk_add_f32 v[86:87], v[86:87], v[106:107]
	v_pk_add_f32 v[84:85], v[84:85], v[104:105]
	global_store_dwordx4 v[96:97], v[84:87], off offset:512
	s_waitcnt vmcnt(7)
	v_pk_add_f32 v[78:79], v[78:79], v[114:115]
	v_pk_add_f32 v[76:77], v[76:77], v[112:113]
	v_lshl_add_u64 v[80:81], v[80:81], 0, v[134:135]
	global_store_dwordx4 v[80:81], v[76:79], off
	s_waitcnt vmcnt(7)
	v_pk_add_f32 v[74:75], v[74:75], v[118:119]
	v_pk_add_f32 v[72:73], v[72:73], v[116:117]
	global_store_dwordx4 v[80:81], v[72:75], off offset:64
	s_waitcnt vmcnt(7)
	v_pk_add_f32 v[70:71], v[70:71], v[122:123]
	v_pk_add_f32 v[68:69], v[68:69], v[120:121]
	global_store_dwordx4 v[80:81], v[68:71], off offset:512
	s_waitcnt vmcnt(7)
; #define PG8_BAR __builtin_amdgcn_s_barrier()
; template <class Epi, class Sched, bool ALIGN_EPI = false, bool SP2 = false>
; __device__ __forceinline__ void gemm_phase(PG8_LAS unsigned char* lds, const Gemm g, const Sched& S, const Epi& E) {
;     ...
;         if constexpr (ALIGN_EPI) { if (wr == 0) PG8_BAR; }
;         if constexpr (!Epi::AFTER_DRAIN) { E(acc, cur, wr, wc, fr, fq); S.done(cur); }
;         if (!has_next) break;
; #pragma unroll
;         for (int a = 0; a < 2; ++a)
; #pragma unroll
;             for (int b = 0; b < 2; ++b)
; #pragma unroll
;                 for (int m = 0; m < 4; ++m)
; #pragma unroll
;                     for (int n = 0; n < 2; ++n) acc[a][b][m][n] = (f32x4){0.f, 0.f, 0.f, 0.f};
;         cur = nxt; cA = nA; cB = nB; ++ui;
;         if constexpr (ALIGN_EPI) { if (wr == 1) PG8_BAR; }
;     __device__ __forceinline__ void operator()(const f32x4 (&acc)[2][2][4][2], const pg8::Unit& u, int wr, int wc, int fr, int fq) const {
;     ...
;         for (int ai = 0; ai < 2; ++ai)
; #pragma unroll
;             for (int mh = 0; mh < 2; ++mh) {
;                 f32x4 xi[2][2][2];
; #pragma unroll
;                 for (int m = 0; m < 2; ++m)
; #pragma unroll
;                     for (int bj = 0; bj < 2; ++bj)
; #pragma unroll
;                         for (int n = 0; n < 2; ++n) xi[m][bj][n] = *(const f32x4*)(Xin + (size_t)(row0 + ai * 128 + (2 * mh + m) * 16) * D + col0 + bj * 128 + n * 16);
;                 __builtin_amdgcn_sched_barrier(0);
; #pragma unroll
;                 for (int m = 0; m < 2; ++m)
; #pragma unroll
;                     for (int bj = 0; bj < 2; ++bj)
; #pragma unroll
;                         for (int n = 0; n < 2; ++n) *(f32x4*)(Xout + (size_t)(row0 + ai * 128 + (2 * mh + m) * 16) * D + col0 + bj * 128 + n * 16) = xi[m][bj][n] + acc[ai][bj][2 * mh + m][n] * scale;
;                 __builtin_amdgcn_sched_barrier(0);
;             }
	v_pk_add_f32 v[66:67], v[66:67], v[126:127]
	v_pk_add_f32 v[64:65], v[64:65], v[124:125]
	global_store_dwordx4 v[80:81], v[64:67], off offset:576
	s_mov_b64 s[0:1], 0x80000
	v_lshl_add_u64 v[96:97], v[138:139], 0, s[0:1]
	s_mov_b64 s[0:1], 0x90000
	v_lshl_add_u64 v[98:99], v[138:139], 0, s[0:1]
	v_lshl_add_u64 v[76:77], v[136:137], 0, v[96:97]
	v_lshl_add_u64 v[92:93], v[136:137], 0, v[98:99]
	global_load_dwordx4 v[64:67], v[76:77], off
	global_load_dwordx4 v[68:71], v[76:77], off offset:64
	global_load_dwordx4 v[72:75], v[76:77], off offset:512
	s_nop 0
	global_load_dwordx4 v[76:79], v[76:77], off offset:576
	s_nop 0
	global_load_dwordx4 v[80:83], v[92:93], off
	global_load_dwordx4 v[84:87], v[92:93], off offset:64
	global_load_dwordx4 v[88:91], v[92:93], off offset:512
	s_nop 0
	global_load_dwordx4 v[92:95], v[92:93], off offset:576
	s_waitcnt vmcnt(7)
	v_pk_add_f32 v[60:61], v[60:61], v[64:65]
	v_lshl_add_u64 v[64:65], s[2:3], 0, v[96:97]
	v_lshl_add_u64 v[64:65], v[64:65], 0, v[134:135]
	s_waitcnt vmcnt(4)
	v_pk_add_f32 v[50:51], v[50:51], v[78:79]
	v_pk_add_f32 v[48:49], v[48:49], v[76:77]
	global_store_dwordx4 v[64:65], v[48:51], off offset:576
	v_pk_add_f32 v[62:63], v[62:63], v[66:67]
	global_store_dwordx4 v[64:65], v[60:63], off
	v_pk_add_f32 v[58:59], v[58:59], v[70:71]
	v_lshl_add_u64 v[48:49], s[2:3], 0, v[98:99]
	v_pk_add_f32 v[56:57], v[56:57], v[68:69]
	global_store_dwordx4 v[64:65], v[56:59], off offset:64
	v_pk_add_f32 v[54:55], v[54:55], v[74:75]
	v_pk_add_f32 v[52:53], v[52:53], v[72:73]
	global_store_dwordx4 v[64:65], v[52:55], off offset:512
	s_waitcnt vmcnt(7)
	v_pk_add_f32 v[46:47], v[46:47], v[82:83]
	v_pk_add_f32 v[44:45], v[44:45], v[80:81]
	v_lshl_add_u64 v[48:49], v[48:49], 0, v[134:135]
	global_store_dwordx4 v[48:49], v[44:47], off
	s_waitcnt vmcnt(7)
	v_pk_add_f32 v[42:43], v[42:43], v[86:87]
	v_pk_add_f32 v[40:41], v[40:41], v[84:85]
	global_store_dwordx4 v[48:49], v[40:43], off offset:64
	s_waitcnt vmcnt(7)
	v_pk_add_f32 v[38:39], v[38:39], v[90:91]
	v_pk_add_f32 v[36:37], v[36:37], v[88:89]
	global_store_dwordx4 v[48:49], v[36:39], off offset:512
	s_waitcnt vmcnt(7)
	v_pk_add_f32 v[34:35], v[34:35], v[94:95]
	v_pk_add_f32 v[32:33], v[32:33], v[92:93]
	global_store_dwordx4 v[48:49], v[32:35], off offset:576
	s_mov_b64 s[0:1], 0xa0000
	v_lshl_add_u64 v[64:65], v[138:139], 0, s[0:1]
	s_mov_b64 s[0:1], 0xb0000
	v_lshl_add_u64 v[66:67], v[138:139], 0, s[0:1]
	v_lshl_add_u64 v[44:45], v[136:137], 0, v[64:65]
	v_lshl_add_u64 v[60:61], v[136:137], 0, v[66:67]
	global_load_dwordx4 v[32:35], v[44:45], off
	global_load_dwordx4 v[36:39], v[44:45], off offset:64
	global_load_dwordx4 v[40:43], v[44:45], off offset:512
	s_nop 0
	global_load_dwordx4 v[44:47], v[44:45], off offset:576
	s_nop 0
	global_load_dwordx4 v[48:51], v[60:61], off
	global_load_dwordx4 v[52:55], v[60:61], off offset:64
	global_load_dwordx4 v[56:59], v[60:61], off offset:512
	s_nop 0
	global_load_dwordx4 v[60:63], v[60:61], off offset:576
	s_waitcnt vmcnt(7)
	v_pk_add_f32 v[28:29], v[28:29], v[32:33]
	v_lshl_add_u64 v[32:33], s[2:3], 0, v[64:65]
	v_lshl_add_u64 v[32:33], v[32:33], 0, v[134:135]
	s_waitcnt vmcnt(4)
	v_pk_add_f32 v[18:19], v[18:19], v[46:47]
	v_pk_add_f32 v[16:17], v[16:17], v[44:45]
	global_store_dwordx4 v[32:33], v[16:19], off offset:576
	v_pk_add_f32 v[30:31], v[30:31], v[34:35]
	global_store_dwordx4 v[32:33], v[28:31], off
	v_pk_add_f32 v[26:27], v[26:27], v[38:39]
	v_lshl_add_u64 v[16:17], s[2:3], 0, v[66:67]
	v_pk_add_f32 v[24:25], v[24:25], v[36:37]
	global_store_dwordx4 v[32:33], v[24:27], off offset:64
	v_pk_add_f32 v[22:23], v[22:23], v[42:43]
	v_pk_add_f32 v[20:21], v[20:21], v[40:41]
	global_store_dwordx4 v[32:33], v[20:23], off offset:512
	s_waitcnt vmcnt(7)
	v_pk_add_f32 v[14:15], v[14:15], v[50:51]
	v_pk_add_f32 v[12:13], v[12:13], v[48:49]
	v_lshl_add_u64 v[16:17], v[16:17], 0, v[134:135]
	global_store_dwordx4 v[16:17], v[12:15], off
	s_waitcnt vmcnt(7)
	v_pk_add_f32 v[10:11], v[10:11], v[54:55]
	v_pk_add_f32 v[8:9], v[8:9], v[52:53]
	global_store_dwordx4 v[16:17], v[8:11], off offset:64
	s_waitcnt vmcnt(7)
	v_pk_add_f32 v[6:7], v[6:7], v[58:59]
	v_pk_add_f32 v[4:5], v[4:5], v[56:57]
	global_store_dwordx4 v[16:17], v[4:7], off offset:512
	s_waitcnt vmcnt(7)
	v_pk_add_f32 v[2:3], v[2:3], v[62:63]
	v_pk_add_f32 v[0:1], v[0:1], v[60:61]
	global_store_dwordx4 v[16:17], v[0:3], off offset:576
	s_and_b64 vcc, exec, s[4:5]
	s_mov_b64 s[0:1], -1
	s_cbranch_vccnz .LBB0_145
	s_andn2_b64 vcc, exec, s[16:17]
	s_cbranch_vccnz .LBB0_144
	s_barrier
	s_branch .LBB0_144

;     __device__ __forceinline__ void operator()(const f32x4 (&acc)[2][2][4][2], const pg8::Unit& u, int wr, int wc, int fr, int fq) const {
;         const int row0 = u.pm * 256 + wr * 64 + fr, col0 = u.pn * 256 + wc * 32 + 4 * fq;
; #pragma unroll
;         for (int ai = 0; ai < 2; ++ai)
; #pragma unroll
;             for (int mh = 0; mh < 2; ++mh) {
;                 f32x4 xi[2][2][2];
; #pragma unroll
;                 for (int m = 0; m < 2; ++m)
; #pragma unroll
;                     for (int bj = 0; bj < 2; ++bj)
; #pragma unroll
;                         for (int n = 0; n < 2; ++n) xi[m][bj][n] = *(const f32x4*)(Xin + (size_t)(row0 + ai * 128 + (2 * mh + m) * 16) * D + col0 + bj * 128 + n * 16);
;                 __builtin_amdgcn_sched_barrier(0);
; #pragma unroll
;                 for (int m = 0; m < 2; ++m)
; #pragma unroll
;                     for (int bj = 0; bj < 2; ++bj)
; #pragma unroll
;                         for (int n = 0; n < 2; ++n) *(f32x4*)(Xout + (size_t)(row0 + ai * 128 + (2 * mh + m) * 16) * D + col0 + bj * 128 + n * 16) = xi[m][bj][n] + acc[ai][bj][2 * mh + m][n] * scale;
.LBB0_817:
	v_lshl_or_b32 v16, s34, 8, v148
	v_lshl_add_u32 v26, s35, 8, v146
	v_ashrrev_i32_e32 v17, 31, v16
	v_lshlrev_b64 v[16:17], 2, v[16:17]
	v_ashrrev_i32_e32 v27, 31, v26
	v_lshl_add_u64 v[18:19], s[12:13], 0, v[16:17]
	v_lshlrev_b64 v[24:25], 12, v[26:27]
	v_lshl_add_u64 v[150:151], v[18:19], 0, v[24:25]
	global_load_dwordx4 v[40:43], v[150:151], off
	global_load_dwordx4 v[168:171], v[150:151], off offset:64
	global_load_dwordx4 v[172:175], v[150:151], off offset:512
	global_load_dwordx4 v[176:179], v[150:151], off offset:576
	v_or_b32_e32 v150, 16, v26
	v_ashrrev_i32_e32 v151, 31, v150
	v_lshlrev_b64 v[150:151], 12, v[150:151]
	v_lshl_add_u64 v[158:159], v[18:19], 0, v[150:151]
	global_load_dwordx4 v[180:183], v[158:159], off
	global_load_dwordx4 v[184:187], v[158:159], off offset:64
	global_load_dwordx4 v[188:191], v[158:159], off offset:512
	global_load_dwordx4 v[192:195], v[158:159], off offset:576
	v_readlane_b32 s2, v254, 52
	v_readlane_b32 s3, v254, 53
	s_waitcnt vmcnt(7)
	v_pk_add_f32 v[42:43], v[134:135], v[42:43]
	v_pk_add_f32 v[40:41], v[136:137], v[40:41]
	v_lshl_add_u64 v[134:135], s[2:3], 0, v[24:25]
	v_lshl_add_u64 v[134:135], v[134:135], 0, v[16:17]
	global_store_dwordx4 v[134:135], v[40:43], off
	s_nop 1
	s_waitcnt vmcnt(7)
	v_pk_add_f32 v[42:43], v[126:127], v[170:171]
	v_pk_add_f32 v[40:41], v[124:125], v[168:169]
	global_store_dwordx4 v[134:135], v[40:43], off offset:64
	s_nop 1
	s_waitcnt vmcnt(7)
	v_pk_add_f32 v[42:43], v[144:145], v[174:175]
	v_pk_add_f32 v[40:41], v[142:143], v[172:173]
	global_store_dwordx4 v[134:135], v[40:43], off offset:512
	s_nop 1
	s_waitcnt vmcnt(7)
	v_pk_add_f32 v[42:43], v[140:141], v[178:179]
	v_pk_add_f32 v[40:41], v[138:139], v[176:177]
	global_store_dwordx4 v[134:135], v[40:43], off offset:576
	s_nop 1
	s_waitcnt vmcnt(7)
	v_pk_add_f32 v[40:41], v[116:117], v[180:181]
	v_lshl_add_u64 v[116:117], s[2:3], 0, v[150:151]
	v_pk_add_f32 v[42:43], v[118:119], v[182:183]
	v_lshl_add_u64 v[116:117], v[116:117], 0, v[16:17]
	global_store_dwordx4 v[116:117], v[40:43], off
	s_nop 1
	s_waitcnt vmcnt(7)
	v_pk_add_f32 v[42:43], v[110:111], v[186:187]
	v_pk_add_f32 v[40:41], v[108:109], v[184:185]
	global_store_dwordx4 v[116:117], v[40:43], off offset:64
	s_nop 1
	s_waitcnt vmcnt(7)
	v_pk_add_f32 v[42:43], v[122:123], v[190:191]
	v_pk_add_f32 v[40:41], v[120:121], v[188:189]
	global_store_dwordx4 v[116:117], v[40:43], off offset:512
	s_nop 1
	s_waitcnt vmcnt(7)
	v_pk_add_f32 v[42:43], v[114:115], v[194:195]
	v_pk_add_f32 v[40:41], v[112:113], v[192:193]
	global_store_dwordx4 v[116:117], v[40:43], off offset:576
	s_nop 1
	v_or_b32_e32 v40, 32, v26
	v_or_b32_e32 v26, 48, v26
	v_ashrrev_i32_e32 v41, 31, v40
	v_ashrrev_i32_e32 v27, 31, v26
	v_lshlrev_b64 v[142:143], 12, v[40:41]
	v_lshlrev_b64 v[26:27], 12, v[26:27]
	v_lshl_add_u64 v[116:117], v[18:19], 0, v[142:143]
	v_lshl_add_u64 v[138:139], v[18:19], 0, v[26:27]
	global_load_dwordx4 v[40:43], v[116:117], off
	global_load_dwordx4 v[108:111], v[116:117], off offset:64
	global_load_dwordx4 v[112:115], v[116:117], off offset:512
	s_nop 0
	global_load_dwordx4 v[116:119], v[116:117], off offset:576
	s_nop 0
	global_load_dwordx4 v[120:123], v[138:139], off
	global_load_dwordx4 v[124:127], v[138:139], off offset:64
	global_load_dwordx4 v[134:137], v[138:139], off offset:512
	s_nop 0
	global_load_dwordx4 v[138:141], v[138:139], off offset:576
	s_waitcnt vmcnt(7)
	v_pk_add_f32 v[40:41], v[100:101], v[40:41]
	v_lshl_add_u64 v[100:101], s[2:3], 0, v[142:143]
	v_pk_add_f32 v[42:43], v[102:103], v[42:43]
	v_lshl_add_u64 v[100:101], v[100:101], 0, v[16:17]
	global_store_dwordx4 v[100:101], v[40:43], off
	v_lshl_add_u64 v[26:27], s[2:3], 0, v[26:27]
	v_lshl_add_u64 v[26:27], v[26:27], 0, v[16:17]
	s_waitcnt vmcnt(7)
	v_pk_add_f32 v[42:43], v[94:95], v[110:111]
	v_pk_add_f32 v[40:41], v[92:93], v[108:109]
	global_store_dwordx4 v[100:101], v[40:43], off offset:64
	s_nop 1
	s_waitcnt vmcnt(7)
	v_pk_add_f32 v[42:43], v[106:107], v[114:115]
	v_pk_add_f32 v[40:41], v[104:105], v[112:113]
	global_store_dwordx4 v[100:101], v[40:43], off offset:512
	s_nop 1
	s_waitcnt vmcnt(7)
	v_pk_add_f32 v[42:43], v[98:99], v[118:119]
	v_pk_add_f32 v[40:41], v[96:97], v[116:117]
	global_store_dwordx4 v[100:101], v[40:43], off offset:576
	s_nop 1
	s_waitcnt vmcnt(7)
	v_pk_add_f32 v[42:43], v[86:87], v[122:123]
	v_pk_add_f32 v[40:41], v[84:85], v[120:121]
	global_store_dwordx4 v[26:27], v[40:43], off
	s_nop 1
	s_waitcnt vmcnt(7)
	v_pk_add_f32 v[42:43], v[74:75], v[126:127]
	v_pk_add_f32 v[40:41], v[72:73], v[124:125]
	global_store_dwordx4 v[26:27], v[40:43], off offset:64
	s_nop 1
	s_waitcnt vmcnt(7)
	v_pk_add_f32 v[42:43], v[90:91], v[136:137]
	v_pk_add_f32 v[40:41], v[88:89], v[134:135]
	global_store_dwordx4 v[26:27], v[40:43], off offset:512
	s_nop 1
	s_waitcnt vmcnt(7)
; #define PG8_BAR __builtin_amdgcn_s_barrier()
; template <class Epi, class Sched, bool ALIGN_EPI = false, bool SP2 = false>
; __device__ __forceinline__ void gemm_phase(PG8_LAS unsigned char* lds, const Gemm g, const Sched& S, const Epi& E) {
;     ...
;         if constexpr (ALIGN_EPI) { if (wr == 0) PG8_BAR; }
;         if constexpr (!Epi::AFTER_DRAIN) { E(acc, cur, wr, wc, fr, fq); S.done(cur); }
;         if (!has_next) break;
; #pragma unroll
;         for (int a = 0; a < 2; ++a)
; #pragma unroll
;             for (int b = 0; b < 2; ++b)
; #pragma unroll
;                 for (int m = 0; m < 4; ++m)
; #pragma unroll
;                     for (int n = 0; n < 2; ++n) acc[a][b][m][n] = (f32x4){0.f, 0.f, 0.f, 0.f};
;         cur = nxt; cA = nA; cB = nB; ++ui;
;         if constexpr (ALIGN_EPI) { if (wr == 1) PG8_BAR; }
;     __device__ __forceinline__ void operator()(const f32x4 (&acc)[2][2][4][2], const pg8::Unit& u, int wr, int wc, int fr, int fq) const {
;     ...
;         for (int ai = 0; ai < 2; ++ai)
; #pragma unroll
;             for (int mh = 0; mh < 2; ++mh) {
;                 f32x4 xi[2][2][2];
; #pragma unroll
;                 for (int m = 0; m < 2; ++m)
; #pragma unroll
;                     for (int bj = 0; bj < 2; ++bj)
; #pragma unroll
;                         for (int n = 0; n < 2; ++n) xi[m][bj][n] = *(const f32x4*)(Xin + (size_t)(row0 + ai * 128 + (2 * mh + m) * 16) * D + col0 + bj * 128 + n * 16);
;                 __builtin_amdgcn_sched_barrier(0);
; #pragma unroll
;                 for (int m = 0; m < 2; ++m)
; #pragma unroll
;                     for (int bj = 0; bj < 2; ++bj)
; #pragma unroll
;                         for (int n = 0; n < 2; ++n) *(f32x4*)(Xout + (size_t)(row0 + ai * 128 + (2 * mh + m) * 16) * D + col0 + bj * 128 + n * 16) = xi[m][bj][n] + acc[ai][bj][2 * mh + m][n] * scale;
;                 __builtin_amdgcn_sched_barrier(0);
;             }
	v_pk_add_f32 v[42:43], v[82:83], v[140:141]
	v_pk_add_f32 v[40:41], v[80:81], v[138:139]
	global_store_dwordx4 v[26:27], v[40:43], off offset:576
	s_mov_b64 s[0:1], 0x80000
	v_lshl_add_u64 v[26:27], v[24:25], 0, s[0:1]
	s_mov_b64 s[0:1], 0x90000
	v_lshl_add_u64 v[104:105], v[24:25], 0, s[0:1]
	v_lshl_add_u64 v[84:85], v[18:19], 0, v[26:27]
	v_lshl_add_u64 v[100:101], v[18:19], 0, v[104:105]
	global_load_dwordx4 v[40:43], v[84:85], off
	global_load_dwordx4 v[72:75], v[84:85], off offset:64
	global_load_dwordx4 v[80:83], v[84:85], off offset:512
	s_nop 0
	global_load_dwordx4 v[84:87], v[84:85], off offset:576
	s_nop 0
	global_load_dwordx4 v[88:91], v[100:101], off
	global_load_dwordx4 v[92:95], v[100:101], off offset:64
	global_load_dwordx4 v[96:99], v[100:101], off offset:512
	s_nop 0
	global_load_dwordx4 v[100:103], v[100:101], off offset:576
	v_lshl_add_u64 v[26:27], s[2:3], 0, v[26:27]
	s_waitcnt vmcnt(7)
	v_pk_add_f32 v[42:43], v[66:67], v[42:43]
	v_pk_add_f32 v[40:41], v[64:65], v[40:41]
	v_lshl_add_u64 v[26:27], v[26:27], 0, v[16:17]
	global_store_dwordx4 v[26:27], v[40:43], off
	s_nop 1
	s_waitcnt vmcnt(7)
	v_pk_add_f32 v[42:43], v[62:63], v[74:75]
	v_pk_add_f32 v[40:41], v[60:61], v[72:73]
	global_store_dwordx4 v[26:27], v[40:43], off offset:64
	s_nop 1
	s_waitcnt vmcnt(7)
	v_pk_add_f32 v[42:43], v[78:79], v[82:83]
	v_pk_add_f32 v[40:41], v[76:77], v[80:81]
	global_store_dwordx4 v[26:27], v[40:43], off offset:512
	s_nop 1
	s_waitcnt vmcnt(7)
	v_pk_add_f32 v[42:43], v[70:71], v[86:87]
	v_pk_add_f32 v[40:41], v[68:69], v[84:85]
	global_store_dwordx4 v[26:27], v[40:43], off offset:576
	v_lshl_add_u64 v[26:27], s[2:3], 0, v[104:105]
	v_lshl_add_u64 v[26:27], v[26:27], 0, v[16:17]
	s_waitcnt vmcnt(7)
	v_pk_add_f32 v[42:43], v[54:55], v[90:91]
	v_pk_add_f32 v[40:41], v[52:53], v[88:89]
	global_store_dwordx4 v[26:27], v[40:43], off
	s_nop 1
	s_waitcnt vmcnt(7)
	v_pk_add_f32 v[42:43], v[46:47], v[94:95]
	v_pk_add_f32 v[40:41], v[44:45], v[92:93]
	global_store_dwordx4 v[26:27], v[40:43], off offset:64
	s_nop 1
	s_waitcnt vmcnt(7)
	v_pk_add_f32 v[42:43], v[58:59], v[98:99]
	v_pk_add_f32 v[40:41], v[56:57], v[96:97]
	global_store_dwordx4 v[26:27], v[40:43], off offset:512
	s_nop 1
	s_waitcnt vmcnt(7)
	v_pk_add_f32 v[42:43], v[50:51], v[102:103]
	v_pk_add_f32 v[40:41], v[48:49], v[100:101]
	global_store_dwordx4 v[26:27], v[40:43], off offset:576
	s_mov_b64 s[0:1], 0xa0000
	v_lshl_add_u64 v[68:69], v[24:25], 0, s[0:1]
	s_mov_b64 s[0:1], 0xb0000
	v_lshl_add_u64 v[70:71], v[24:25], 0, s[0:1]
	v_lshl_add_u64 v[26:27], v[18:19], 0, v[68:69]
	v_lshl_add_u64 v[18:19], v[18:19], 0, v[70:71]
	global_load_dwordx4 v[40:43], v[26:27], off
	global_load_dwordx4 v[44:47], v[26:27], off offset:64
	global_load_dwordx4 v[48:51], v[26:27], off offset:512
	global_load_dwordx4 v[52:55], v[26:27], off offset:576
	s_nop 0
	global_load_dwordx4 v[24:27], v[18:19], off
	global_load_dwordx4 v[56:59], v[18:19], off offset:64
	global_load_dwordx4 v[60:63], v[18:19], off offset:512
	global_load_dwordx4 v[64:67], v[18:19], off offset:576
	v_lshl_add_u64 v[18:19], s[2:3], 0, v[68:69]
	s_waitcnt vmcnt(7)
	v_pk_add_f32 v[28:29], v[28:29], v[40:41]
	v_lshl_add_u64 v[40:41], v[18:19], 0, v[16:17]
	s_waitcnt vmcnt(6)
	v_pk_add_f32 v[22:23], v[22:23], v[46:47]
	v_pk_add_f32 v[20:21], v[20:21], v[44:45]
	global_store_dwordx4 v[40:41], v[20:23], off offset:64
	s_waitcnt vmcnt(6)
	v_pk_add_f32 v[18:19], v[36:37], v[48:49]
	v_pk_add_f32 v[30:31], v[30:31], v[42:43]
	v_pk_add_f32 v[20:21], v[38:39], v[50:51]
	global_store_dwordx4 v[40:41], v[18:21], off offset:512
	s_waitcnt vmcnt(5)
	v_pk_add_f32 v[14:15], v[14:15], v[26:27]
	v_pk_add_f32 v[12:13], v[12:13], v[24:25]
	v_pk_add_f32 v[20:21], v[34:35], v[54:55]
	v_pk_add_f32 v[18:19], v[32:33], v[52:53]
	global_store_dwordx4 v[40:41], v[18:21], off offset:576
	global_store_dwordx4 v[40:41], v[28:31], off
	s_waitcnt vmcnt(6)
	v_pk_add_f32 v[10:11], v[10:11], v[58:59]
	v_pk_add_f32 v[8:9], v[8:9], v[56:57]
	v_lshl_add_u64 v[18:19], s[2:3], 0, v[70:71]
	v_lshl_add_u64 v[16:17], v[18:19], 0, v[16:17]
	global_store_dwordx4 v[16:17], v[12:15], off
	global_store_dwordx4 v[16:17], v[8:11], off offset:64
	s_waitcnt vmcnt(7)
	v_pk_add_f32 v[6:7], v[6:7], v[62:63]
	v_pk_add_f32 v[4:5], v[4:5], v[60:61]
	global_store_dwordx4 v[16:17], v[4:7], off offset:512
	s_waitcnt vmcnt(7)
	v_pk_add_f32 v[2:3], v[2:3], v[66:67]
	v_pk_add_f32 v[0:1], v[0:1], v[64:65]
	global_store_dwordx4 v[16:17], v[0:3], off offset:576
	s_and_b64 vcc, exec, s[4:5]
	s_mov_b64 s[0:1], -1
	s_cbranch_vccnz .LBB0_800
	s_andn2_b64 vcc, exec, s[16:17]
	s_cbranch_vccnz .LBB0_799
	s_barrier
	s_branch .LBB0_799
